# attention phase rewritten: each wave owns two adjacent query blocks sharing K/V tile loads (single rep, 2 heads per WG)
# speedup vs baseline: 1.0078x; 1.0078x over previous
; #define LAS __attribute__((address_space(3)))
; __device__ __forceinline__ void attn_phase(const bf16_t* Z, const bf16_t* Kb, const bf16_t* Vb, unsigned* MASKb, unsigned* itemcnt, bf16_t* Y, LAS unsigned char* lds, int wave, int lane, int bid, int G) {
;     const int h = wave & 3, half = wave >> 2, ql = lane & 31, hi = lane >> 5;
;     LAS float* mo = (LAS float*)lds + h * 2048;
;     LAS float* mml = (LAS float*)(lds + 32768) + h * 128;
;     LAS bf16_t* ost = (LAS bf16_t*)(lds + 36864) + h * (32 * 72);
;     const unsigned NEGB = __float_as_uint(NEGF);
;     for (int pu = bid; pu < 256; pu += G) {
;         const int b = pu & 3, jj = pu >> 2;
;         for (int rep = 0; rep < 2; ++rep) {
;             const int qb = rep ? jj : 127 - jj;
;             const int NT = qb + 1, n0 = (NT + 1) >> 1, tb = half ? n0 : 0, te = half ? NT : n0;
;             if (wave == 0) {
;                 unsigned* c0 = itemcnt + (2 * qb) * 4 + b; unsigned* c1 = c0 + 4; unsigned spins = 0;
;                 while ((unsigned)__builtin_amdgcn_readfirstlane(__hip_atomic_load(c0, __ATOMIC_RELAXED, __HIP_MEMORY_SCOPE_AGENT)) < 8u ||
;                        (unsigned)__builtin_amdgcn_readfirstlane(__hip_atomic_load(c1, __ATOMIC_RELAXED, __HIP_MEMORY_SCOPE_AGENT)) < 8u) { __builtin_amdgcn_s_sleep(4); if (++spins > (1u << 22)) break; }
;                 __builtin_amdgcn_fence(__ATOMIC_ACQUIRE, "agent");
;             }
;             __syncthreads();
.LBB0_23:
	s_add_i32 s0, s64, -1
	s_mul_hi_i32 s1, s0, 0x2aaaaaab
	s_lshr_b32 s4, s1, 31
	s_add_i32 s6, s1, s4
	s_mul_i32 s1, s6, 6
	s_mov_b32 s4, s6
	s_sub_i32 s6, s0, s1
	v_writelane_b32 v255, s4, 28
	s_add_u32 s0, s78, 0x6400000
	s_addc_u32 s1, s79, 0
	v_writelane_b32 v255, s5, 29
	v_writelane_b32 v255, s0, 30
	s_nop 1
	v_writelane_b32 v255, s1, 31
	s_add_u32 s0, s78, 0x8400000
	s_addc_u32 s1, s79, 0
	s_add_u32 s4, s78, 0x3c00000
	s_addc_u32 s5, s79, 0
	v_writelane_b32 v255, s4, 32
	s_nop 1
	v_writelane_b32 v255, s5, 33
	s_add_u32 s4, s78, 0xe400000
	s_addc_u32 s5, s79, 0
	v_writelane_b32 v255, s4, 34
	s_nop 1
	v_writelane_b32 v255, s5, 35
	s_add_u32 s4, s78, 0xec00000
	s_addc_u32 s5, s79, 0
	v_writelane_b32 v255, s4, 36
	s_cmp_lt_i32 s6, 1
	s_nop 0
	v_writelane_b32 v255, s5, 37
	v_writelane_b32 v255, s6, 38
	s_mov_b64 s[6:7], 0
	v_writelane_b32 v255, s6, 39
	s_mov_b64 s[4:5], -1
	s_nop 0
	v_writelane_b32 v255, s7, 40
	s_cbranch_scc1 .LBB0_252
	s_add_u32 s4, s78, 0x3400000
	s_addc_u32 s5, s79, 0
	v_writelane_b32 v255, s4, 41
	s_nop 1
	v_writelane_b32 v255, s5, 42
	s_nop 0
	v_readlane_b32 s4, v255, 38
	s_cmp_gt_i32 s4, 1
	v_writelane_b32 v255, s64, 43
	s_cbranch_scc0 .LBB0_109
	s_cmp_eq_u32 s4, 2
	s_mov_b64 s[4:5], -1
	s_cbranch_scc0 .LBB0_111
	v_readlane_b32 s18, v255, 30
	s_cmpk_gt_i32 s76, 0xff
	v_readlane_b32 s19, v255, 31
	s_cbranch_scc1 .LBB0_110
	v_readlane_b32 s4, v255, 28
	v_readlane_b32 s5, v255, 29
	s_lshl_b32 s4, s4, 10
	s_ashr_i32 s5, s4, 31
	s_lshl_b64 s[4:5], s[4:5], 2
	s_add_u32 s4, s78, s4
	s_addc_u32 s5, s79, s5
	s_add_u32 s22, s4, 0xfa08000
	v_readlane_b32 s11, v255, 21
	s_addc_u32 s23, s5, 0
	s_lshr_b32 s6, s11, 2
	s_lshl_b32 s6, s6, 1
	s_bitcmp1_b32 s11, 0
	s_addc_u32 s6, s6, 0
	s_lshl_b32 s4, s6, 13
	s_add_i32 s7, s4, 0
	s_mul_i32 s4, s6, 0xfffff200
	s_add_i32 s8, s7, s4
	s_lshl_b32 s4, s6, 12
	s_sub_i32 s9, s8, s4
	v_and_b32_e32 v138, 31, v166
	v_readlane_b32 s4, v255, 41
	v_lshlrev_b32_e32 v0, 2, v138
	v_readlane_b32 s5, v255, 42
	s_waitcnt vmcnt(5)
	v_ashrrev_i32_e32 v8, 5, v166
	s_waitcnt vmcnt(4)
	v_lshlrev_b32_e32 v2, 3, v8
	v_lshl_add_u64 v[140:141], s[4:5], 0, v[0:1]
	v_readlane_b32 s4, v255, 34
	v_lshlrev_b32_e32 v0, 5, v138
	v_readlane_b32 s5, v255, 35
	s_bitcmp0_b32 s11, 1
	v_ashrrev_i32_e32 v3, 31, v2
	v_lshl_add_u64 v[4:5], s[4:5], 0, v[0:1]
	v_readlane_b32 s4, v255, 32
	s_cselect_b64 s[12:13], -1, 0
	s_cmp_eq_u32 s11, 0
	v_lshlrev_b64 v[6:7], 1, v[2:3]
	v_readlane_b32 s5, v255, 33
	v_lshlrev_b32_e32 v3, 2, v166
	s_cselect_b64 s[14:15], -1, 0
	s_bfe_u32 s10, s76, 0x10002
	s_lshl_b32 s10, s10, 1
	s_bitcmp1_b32 s6, 0
	s_addc_u32 s10, s10, 0
	s_lshl_b32 s10, s10, 18
	v_lshl_add_u64 v[142:143], v[4:5], 0, v[6:7]
	v_lshl_add_u64 v[4:5], s[4:5], 0, v[0:1]
	s_nop 0
	v_add_u32_e32 v158, s9, v3
	v_ashrrev_i32_e32 v146, 1, v166
	s_movk_i32 s9, 0x90
	v_lshlrev_b32_e32 v0, 6, v166
	v_lshl_add_u64 v[144:145], v[4:5], 0, v[6:7]
	s_bitcmp1_b32 s11, 1
	v_mul_u32_u24_e32 v4, 0x90, v138
	v_mul_lo_u32 v5, v146, s9
	v_and_b32_e32 v0, 64, v0
	s_cselect_b64 s[16:17], -1, 0
	v_add3_u32 v159, s8, v5, v0
	v_add3_u32 v161, s8, v4, v2
	s_bfe_u32 s8, s76, 0x10002
	s_lshl_b32 s8, s8, 1
	s_bitcmp1_b32 s6, 0
	s_addc_u32 s8, s8, 0
	s_lshl_b32 s8, s8, 7
	s_add_u32 s6, s0, s8
	v_add_u32_e32 v160, s7, v3
	s_addc_u32 s7, s1, 0
	v_lshl_add_u64 v[148:149], s[6:7], 0, v[6:7]
	s_add_u32 s6, s18, s8
	s_addc_u32 s7, s19, 0
	v_mov_b32_e32 v62, 0
	v_lshlrev_b32_e32 v139, 2, v8
	v_cmp_gt_u32_e64 s[4:5], 32, v166
	v_ashrrev_i32_e32 v147, 31, v146
	v_lshl_add_u64 v[150:151], s[6:7], 0, v[0:1]
	s_lshl_b32 s24, s10, 1
	s_mov_b32 s25, s76
.Lat_pu:
	s_and_b32 s18, s25, 3
	s_lshr_b32 s20, s25, 3
	v_readlane_b32 s21, v255, 21
	s_sub_i32 s29, 63, s20
	s_lshl_b32 s6, s18, 2
	s_add_u32 s27, s22, s6
	s_addc_u32 s28, s23, 0
	s_lshr_b32 s21, s21, 2
	s_cmp_eq_u32 s21, 0
	s_cselect_b32 s35, s29, s20
	s_andn2_b64 vcc, exec, s[14:15]
	s_cbranch_vccnz .Lat_nospin
	s_lshl_b32 s8, s29, 6
	s_add_u32 s8, s27, s8
	s_addc_u32 s9, s28, 0
	s_lshl_b32 s10, s20, 6
	s_add_u32 s10, s27, s10
	s_addc_u32 s11, s28, 0
	s_mov_b32 s19, 0x400000
.Lat_spin:
	global_load_dword v0, v1, s[8:9] sc1
	global_load_dword v2, v1, s[8:9] offset:16 sc1
	global_load_dword v3, v1, s[8:9] offset:32 sc1
	global_load_dword v4, v1, s[8:9] offset:48 sc1
	global_load_dword v5, v1, s[10:11] sc1
	global_load_dword v6, v1, s[10:11] offset:16 sc1
	global_load_dword v7, v1, s[10:11] offset:32 sc1
	global_load_dword v8, v1, s[10:11] offset:48 sc1
	s_waitcnt vmcnt(0)
	v_min3_u32 v0, v0, v2, v3
	v_min3_u32 v4, v4, v5, v6
	v_min3_u32 v0, v0, v7, v8
	v_min_u32_e32 v0, v0, v4
	s_nop 0
	v_readfirstlane_b32 s21, v0
	s_cmp_gt_u32 s21, 7
	s_cbranch_scc1 .Lat_spin_done
	s_sleep 4
	s_add_i32 s19, s19, -1
	s_cmp_eq_u32 s19, 0
	s_cbranch_scc0 .Lat_spin

; __device__ __forceinline__ void attn_phase(const bf16_t* Z, const bf16_t* Kb, const bf16_t* Vb, unsigned* MASKb, unsigned* itemcnt, bf16_t* Y, LAS unsigned char* lds, int wave, int lane, int bid, int G) {
;     ...
;             const size_t rowq = (size_t)b * SEQ + qb * 32 + ql;
;             const bf16_t* zq = Z + rowq * NZ + 1280 + h * 64 + hi * 8;
;             bf16x8 qf[4];
; #pragma unroll
;             for (int c = 0; c < 4; ++c) qf[c] = *(const bf16x8*)(zq + 16 * c);
;             unsigned* mrow = MASKb + ((size_t)(b * 128 + qb) * 128) * 32 + ql;
;             const bf16_t* kb = Kb + ((size_t)(b * 4 + h) * 128) * 2048 + ql * 16 + hi * 8;
;             const bf16_t* vb = Vb + ((size_t)(b * 4 + h) * 128) * 2048 + ql * 16 + hi * 8;
;             f32x16 o0, o1;
; #pragma unroll
;             for (int r = 0; r < 16; ++r) { o0[r] = 0.f; o1[r] = 0.f; }
;             float m = NEGF, l = 0.f;
;             bf16x8 kA[4], kB[4]; bf16x8 vA[2][2], vB[2][2]; unsigned mA = 0u, mB = 0u;
.Lat_nospin:
	s_barrier
	s_lshl_b32 s8, s18, 21
	s_or_b32 s8, s8, s24
	v_readlane_b32 s6, v255, 34
	v_readlane_b32 s7, v255, 35
	v_readlane_b32 s10, v255, 32
	v_readlane_b32 s11, v255, 33
	v_readlane_b32 s30, v255, 41
	v_readlane_b32 s31, v255, 42
	s_add_u32 s6, s6, s8
	s_addc_u32 s7, s7, 0
	s_add_u32 s10, s10, s8
	s_addc_u32 s11, s11, 0
	s_lshl_b32 s20, s18, 7
	s_lshl_b32 s21, s35, 1
	s_add_i32 s20, s20, s21
	s_lshl_b32 s20, s20, 14
	s_add_u32 s20, s30, s20
	s_addc_u32 s21, s31, 0
	s_add_i32 s19, s35, 1
	s_lshl_b32 s9, s19, 1
	s_and_b64 s[30:31], s[12:13], exec
	s_cselect_b32 s8, 0, s19
	s_cselect_b32 s19, s19, s9
	s_add_i32 s9, s19, -1
	s_lshl_b32 s35, s35, 1
	s_lshl_b32 s26, s18, 12
	s_lshl_b32 s34, s35, 5
	s_add_i32 s18, s34, s26
	v_or_b32_e32 v0, s18, v138
	v_mad_u64_u32 v[34:35], vcc, v0, s33, v[148:149]
	s_mov_b32 s30, 0x30000
	s_mov_b32 s31, 0
	global_load_dwordx4 v[82:85], v[34:35], off offset:2560
	global_load_dwordx4 v[86:89], v[34:35], off offset:2592
	global_load_dwordx4 v[90:93], v[34:35], off offset:2624
	global_load_dwordx4 v[94:97], v[34:35], off offset:2656
	v_lshl_add_u64 v[36:37], v[34:35], 0, s[30:31]
	global_load_dwordx4 v[114:117], v[36:37], off offset:2560
	global_load_dwordx4 v[118:121], v[36:37], off offset:2592
	global_load_dwordx4 v[122:125], v[36:37], off offset:2624
	global_load_dwordx4 v[126:129], v[36:37], off offset:2656
	v_lshlrev_b32_e32 v175, 2, v139
	v_lshl_add_u32 v175, v138, 5, v175
	v_lshlrev_b32_e32 v176, 2, v138
	v_add_u32_e32 v177, 0x4000, v176
	s_lshl_b32 s27, s8, 12
	s_add_u32 s28, s6, s27
	s_addc_u32 s29, s7, 0
	global_load_dwordx4 v[66:69], v175, s[28:29]
	global_load_dwordx4 v[70:73], v175, s[28:29] offset:1024
	global_load_dwordx4 v[74:77], v175, s[28:29] offset:2048
	global_load_dwordx4 v[78:81], v175, s[28:29] offset:3072
	s_lshl_b32 s34, s8, 7
	s_add_u32 s30, s20, s34
	s_addc_u32 s31, s21, 0
	global_load_dword v173, v176, s[30:31] sc1
	global_load_dword v174, v177, s[30:31] sc1
	s_add_u32 s28, s10, s27
	s_addc_u32 s29, s11, 0
	global_load_dwordx4 v[98:101], v175, s[28:29]
	global_load_dwordx4 v[102:105], v175, s[28:29] offset:1024
	global_load_dwordx4 v[106:109], v175, s[28:29] offset:2048
	global_load_dwordx4 v[110:113], v175, s[28:29] offset:3072
	v_mov_b32_e32 v2, 0
	v_mov_b32_e32 v3, 0
	v_mov_b32_e32 v4, 0
	v_mov_b32_e32 v5, 0
	v_mov_b32_e32 v6, 0
	v_mov_b32_e32 v7, 0
	v_mov_b32_e32 v8, 0
	v_mov_b32_e32 v9, 0
	v_mov_b32_e32 v10, 0
	v_mov_b32_e32 v11, 0
	v_mov_b32_e32 v12, 0
	v_mov_b32_e32 v13, 0
	v_mov_b32_e32 v14, 0
	v_mov_b32_e32 v15, 0
	v_mov_b32_e32 v16, 0
	v_mov_b32_e32 v17, 0
	v_mov_b32_e32 v18, 0
	v_mov_b32_e32 v19, 0
	v_mov_b32_e32 v20, 0
	v_mov_b32_e32 v21, 0
	v_mov_b32_e32 v22, 0
	v_mov_b32_e32 v23, 0
	v_mov_b32_e32 v24, 0
	v_mov_b32_e32 v25, 0
	v_mov_b32_e32 v26, 0
	v_mov_b32_e32 v27, 0
	v_mov_b32_e32 v28, 0
	v_mov_b32_e32 v29, 0
	v_mov_b32_e32 v30, 0
	v_mov_b32_e32 v31, 0
	v_mov_b32_e32 v32, 0
	v_mov_b32_e32 v33, 0
	v_mov_b32_e32 v198, 0
	v_mov_b32_e32 v199, 0
	v_mov_b32_e32 v200, 0
	v_mov_b32_e32 v201, 0
	v_mov_b32_e32 v202, 0
	v_mov_b32_e32 v203, 0
	v_mov_b32_e32 v204, 0
	v_mov_b32_e32 v205, 0
	v_mov_b32_e32 v206, 0
	v_mov_b32_e32 v207, 0
	v_mov_b32_e32 v208, 0
	v_mov_b32_e32 v209, 0
	v_mov_b32_e32 v210, 0
	v_mov_b32_e32 v211, 0
	v_mov_b32_e32 v212, 0
	v_mov_b32_e32 v213, 0
	v_mov_b32_e32 v220, 0
	v_mov_b32_e32 v221, 0
	v_mov_b32_e32 v222, 0
	v_mov_b32_e32 v223, 0
	v_mov_b32_e32 v224, 0
	v_mov_b32_e32 v225, 0
	v_mov_b32_e32 v226, 0
	v_mov_b32_e32 v227, 0
	v_mov_b32_e32 v228, 0
	v_mov_b32_e32 v229, 0
	v_mov_b32_e32 v230, 0
	v_mov_b32_e32 v231, 0
	v_mov_b32_e32 v232, 0
	v_mov_b32_e32 v233, 0
	v_mov_b32_e32 v234, 0
	v_mov_b32_e32 v235, 0
	v_mov_b32_e32 v167, 0
	v_mov_b32_e32 v169, 0
	v_mov_b32_e32 v168, 0xf149f2ca
	v_mov_b32_e32 v170, 0xf149f2ca
.Lat_loop:
	s_waitcnt vmcnt(6)
	v_mfma_f32_32x32x16_bf16 v[34:49], v[66:69], v[82:85], 0
	v_mfma_f32_32x32x16_bf16 v[34:49], v[70:73], v[86:89], v[34:49]
	v_mfma_f32_32x32x16_bf16 v[34:49], v[74:77], v[90:93], v[34:49]
	v_mfma_f32_32x32x16_bf16 v[34:49], v[78:81], v[94:97], v[34:49]
	v_mfma_f32_32x32x16_bf16 v[50:65], v[66:69], v[114:117], 0
	v_mfma_f32_32x32x16_bf16 v[50:65], v[70:73], v[118:121], v[50:65]
	v_mfma_f32_32x32x16_bf16 v[50:65], v[74:77], v[122:125], v[50:65]
	v_mfma_f32_32x32x16_bf16 v[50:65], v[78:81], v[126:129], v[50:65]
	s_add_i32 s26, s8, 1
	s_min_i32 s26, s26, s9
	s_lshl_b32 s27, s26, 12
	s_add_u32 s28, s6, s27
	s_addc_u32 s29, s7, 0
	s_lshl_b32 s34, s26, 7
	s_add_u32 s30, s20, s34
	s_addc_u32 s31, s21, 0
	s_cmp_gt_u32 s8, s35
	s_cselect_b32 s82, 0, -1
	s_waitcnt vmcnt(4)
	v_lshrrev_b32_e32 v171, v139, v173
	v_lshrrev_b32_e32 v172, v139, v174
	v_and_b32_e32 v171, s82, v171
	global_load_dwordx4 v[66:69], v175, s[28:29]
	global_load_dwordx4 v[70:73], v175, s[28:29] offset:1024
	global_load_dwordx4 v[74:77], v175, s[28:29] offset:2048
	global_load_dwordx4 v[78:81], v175, s[28:29] offset:3072
	global_load_dword v173, v176, s[30:31] sc1
	global_load_dword v174, v177, s[30:31] sc1
	v_bfe_i32 v178, v171, 0, 1
	v_bitop3_b32 v34, v34, s96, v178 bitop3:0xe4
	v_bfe_i32 v180, v171, 1, 1
	v_bitop3_b32 v35, v35, s96, v180 bitop3:0xe4
	v_bfe_i32 v178, v171, 2, 1
	v_bitop3_b32 v36, v36, s96, v178 bitop3:0xe4
	v_bfe_i32 v180, v171, 3, 1
	v_bitop3_b32 v37, v37, s96, v180 bitop3:0xe4
	v_bfe_i32 v178, v171, 8, 1
	v_bitop3_b32 v38, v38, s96, v178 bitop3:0xe4
	v_bfe_i32 v180, v171, 9, 1
	v_bitop3_b32 v39, v39, s96, v180 bitop3:0xe4
	v_bfe_i32 v178, v171, 10, 1
	v_bitop3_b32 v40, v40, s96, v178 bitop3:0xe4
	v_bfe_i32 v180, v171, 11, 1
	v_bitop3_b32 v41, v41, s96, v180 bitop3:0xe4
	v_bfe_i32 v178, v171, 16, 1
	v_bitop3_b32 v42, v42, s96, v178 bitop3:0xe4
	v_bfe_i32 v180, v171, 17, 1
	v_bitop3_b32 v43, v43, s96, v180 bitop3:0xe4
	v_bfe_i32 v178, v171, 18, 1
	v_bitop3_b32 v44, v44, s96, v178 bitop3:0xe4
	v_bfe_i32 v180, v171, 19, 1
	v_bitop3_b32 v45, v45, s96, v180 bitop3:0xe4
	v_bfe_i32 v178, v171, 24, 1
	v_bitop3_b32 v46, v46, s96, v178 bitop3:0xe4
	v_bfe_i32 v180, v171, 25, 1
	v_bitop3_b32 v47, v47, s96, v180 bitop3:0xe4
	v_bfe_i32 v178, v171, 26, 1
	v_bitop3_b32 v48, v48, s96, v178 bitop3:0xe4
	v_bfe_i32 v180, v171, 27, 1
	v_bitop3_b32 v49, v49, s96, v180 bitop3:0xe4
	v_max3_f32 v190, v34, s96, v35
	v_max3_f32 v190, v190, v36, v37
	v_max3_f32 v190, v190, v38, v39
	v_max3_f32 v190, v190, v40, v41
	v_max3_f32 v190, v190, v42, v43
	v_max3_f32 v190, v190, v44, v45
	v_max3_f32 v190, v190, v46, v47
	v_max3_f32 v190, v190, v48, v49
	v_mov_b32_e32 v191, v190
	v_mov_b32_e32 v192, v190
	s_nop 1
	v_permlane32_swap_b32_e32 v191, v192
	v_cndmask_b32_e64 v191, v191, v192, s[4:5]
	v_max3_f32 v193, v168, v190, v191
	v_cmp_gt_f32_e32 vcc, v193, v168
	s_cbranch_vccz .Lat_nors_a
	v_sub_f32_e32 v194, v168, v193
	v_exp_f32_e32 v194, v194
	s_nop 0
	v_pk_mul_f32 v[2:3], v[2:3], v[194:195] op_sel_hi:[1,0]
	v_pk_mul_f32 v[4:5], v[4:5], v[194:195] op_sel_hi:[1,0]
	v_pk_mul_f32 v[6:7], v[6:7], v[194:195] op_sel_hi:[1,0]
	v_pk_mul_f32 v[8:9], v[8:9], v[194:195] op_sel_hi:[1,0]
	v_pk_mul_f32 v[10:11], v[10:11], v[194:195] op_sel_hi:[1,0]
	v_pk_mul_f32 v[12:13], v[12:13], v[194:195] op_sel_hi:[1,0]
	v_pk_mul_f32 v[14:15], v[14:15], v[194:195] op_sel_hi:[1,0]
	v_pk_mul_f32 v[16:17], v[16:17], v[194:195] op_sel_hi:[1,0]
	v_pk_mul_f32 v[18:19], v[18:19], v[194:195] op_sel_hi:[1,0]
	v_pk_mul_f32 v[20:21], v[20:21], v[194:195] op_sel_hi:[1,0]
	v_pk_mul_f32 v[22:23], v[22:23], v[194:195] op_sel_hi:[1,0]
	v_pk_mul_f32 v[24:25], v[24:25], v[194:195] op_sel_hi:[1,0]
	v_pk_mul_f32 v[26:27], v[26:27], v[194:195] op_sel_hi:[1,0]
	v_pk_mul_f32 v[28:29], v[28:29], v[194:195] op_sel_hi:[1,0]
	v_pk_mul_f32 v[30:31], v[30:31], v[194:195] op_sel_hi:[1,0]
	v_pk_mul_f32 v[32:33], v[32:33], v[194:195] op_sel_hi:[1,0]
	v_mul_f32_e32 v167, v167, v194
.Lat_nors_a:
	v_mov_b32_e32 v168, v193
	v_sub_f32_e32 v34, v34, v168
	v_exp_f32_e32 v34, v34
	v_sub_f32_e32 v35, v35, v168
	v_exp_f32_e32 v35, v35
	v_sub_f32_e32 v36, v36, v168
	v_add_f32_e32 v196, v34, v35
	v_exp_f32_e32 v36, v36
	v_sub_f32_e32 v37, v37, v168
	v_add_f32_e32 v196, v196, v36
	v_exp_f32_e32 v37, v37
	v_sub_f32_e32 v38, v38, v168
	v_add_f32_e32 v196, v196, v37
	v_exp_f32_e32 v38, v38
	v_sub_f32_e32 v39, v39, v168
	v_add_f32_e32 v196, v196, v38
	v_exp_f32_e32 v39, v39
	v_sub_f32_e32 v40, v40, v168
	v_add_f32_e32 v196, v196, v39
	v_exp_f32_e32 v40, v40
	v_sub_f32_e32 v41, v41, v168
	v_add_f32_e32 v196, v196, v40
	v_exp_f32_e32 v41, v41
	v_sub_f32_e32 v42, v42, v168
	v_add_f32_e32 v196, v196, v41
	v_exp_f32_e32 v42, v42
	v_sub_f32_e32 v43, v43, v168
	v_add_f32_e32 v196, v196, v42
	v_exp_f32_e32 v43, v43
	v_sub_f32_e32 v44, v44, v168
	v_add_f32_e32 v196, v196, v43
	v_exp_f32_e32 v44, v44
	v_sub_f32_e32 v45, v45, v168
	v_add_f32_e32 v196, v196, v44
	v_exp_f32_e32 v45, v45
	v_sub_f32_e32 v46, v46, v168
	v_add_f32_e32 v196, v196, v45
	v_exp_f32_e32 v46, v46
	v_sub_f32_e32 v47, v47, v168
	v_add_f32_e32 v196, v196, v46
	v_exp_f32_e32 v47, v47
	v_sub_f32_e32 v48, v48, v168
	v_add_f32_e32 v196, v196, v47
	v_exp_f32_e32 v48, v48
	v_sub_f32_e32 v49, v49, v168
	v_add_f32_e32 v196, v196, v48
	v_exp_f32_e32 v49, v49
	s_nop 0
	v_add_f32_e32 v196, v196, v49
	v_add_f32_e32 v167, v167, v196
	v_cvt_pk_bf16_f32 v130, v34, v35
	v_cvt_pk_bf16_f32 v131, v36, v37
	v_cvt_pk_bf16_f32 v132, v38, v39
	v_cvt_pk_bf16_f32 v133, v40, v41
	v_cvt_pk_bf16_f32 v134, v42, v43
	v_cvt_pk_bf16_f32 v135, v44, v45
	v_cvt_pk_bf16_f32 v136, v46, v47
	v_cvt_pk_bf16_f32 v137, v48, v49
	v_bfe_i32 v178, v172, 0, 1
	v_bitop3_b32 v50, v50, s96, v178 bitop3:0xe4
	v_bfe_i32 v180, v172, 1, 1
	v_bitop3_b32 v51, v51, s96, v180 bitop3:0xe4
	v_bfe_i32 v178, v172, 2, 1
	v_bitop3_b32 v52, v52, s96, v178 bitop3:0xe4
	v_bfe_i32 v180, v172, 3, 1
	v_bitop3_b32 v53, v53, s96, v180 bitop3:0xe4
	v_bfe_i32 v178, v172, 8, 1
	v_bitop3_b32 v54, v54, s96, v178 bitop3:0xe4
	v_bfe_i32 v180, v172, 9, 1
	v_bitop3_b32 v55, v55, s96, v180 bitop3:0xe4
	v_bfe_i32 v178, v172, 10, 1
	v_bitop3_b32 v56, v56, s96, v178 bitop3:0xe4
	v_bfe_i32 v180, v172, 11, 1
	v_bitop3_b32 v57, v57, s96, v180 bitop3:0xe4
	v_bfe_i32 v178, v172, 16, 1
	v_bitop3_b32 v58, v58, s96, v178 bitop3:0xe4
	v_bfe_i32 v180, v172, 17, 1
	v_bitop3_b32 v59, v59, s96, v180 bitop3:0xe4
	v_bfe_i32 v178, v172, 18, 1
	v_bitop3_b32 v60, v60, s96, v178 bitop3:0xe4
	v_bfe_i32 v180, v172, 19, 1
	v_bitop3_b32 v61, v61, s96, v180 bitop3:0xe4
	v_bfe_i32 v178, v172, 24, 1
	v_bitop3_b32 v62, v62, s96, v178 bitop3:0xe4
	v_bfe_i32 v180, v172, 25, 1
	v_bitop3_b32 v63, v63, s96, v180 bitop3:0xe4
	v_bfe_i32 v178, v172, 26, 1
	v_bitop3_b32 v64, v64, s96, v178 bitop3:0xe4
	v_bfe_i32 v180, v172, 27, 1
	v_bitop3_b32 v65, v65, s96, v180 bitop3:0xe4
	v_max3_f32 v190, v50, s96, v51
	v_max3_f32 v190, v190, v52, v53
	v_max3_f32 v190, v190, v54, v55
	v_max3_f32 v190, v190, v56, v57
	v_max3_f32 v190, v190, v58, v59
	v_max3_f32 v190, v190, v60, v61
	v_max3_f32 v190, v190, v62, v63
	v_max3_f32 v190, v190, v64, v65
	v_mov_b32_e32 v191, v190
	v_mov_b32_e32 v192, v190
	s_nop 1
	v_permlane32_swap_b32_e32 v191, v192
	v_cndmask_b32_e64 v191, v191, v192, s[4:5]
	v_max3_f32 v193, v170, v190, v191
	v_cmp_gt_f32_e32 vcc, v193, v170
	s_cbranch_vccz .Lat_nors_b
	v_sub_f32_e32 v194, v170, v193
	v_exp_f32_e32 v194, v194
	s_nop 0
	v_pk_mul_f32 v[198:199], v[198:199], v[194:195] op_sel_hi:[1,0]
	v_pk_mul_f32 v[200:201], v[200:201], v[194:195] op_sel_hi:[1,0]
	v_pk_mul_f32 v[202:203], v[202:203], v[194:195] op_sel_hi:[1,0]
	v_pk_mul_f32 v[204:205], v[204:205], v[194:195] op_sel_hi:[1,0]
	v_pk_mul_f32 v[206:207], v[206:207], v[194:195] op_sel_hi:[1,0]
	v_pk_mul_f32 v[208:209], v[208:209], v[194:195] op_sel_hi:[1,0]
	v_pk_mul_f32 v[210:211], v[210:211], v[194:195] op_sel_hi:[1,0]
	v_pk_mul_f32 v[212:213], v[212:213], v[194:195] op_sel_hi:[1,0]
	v_pk_mul_f32 v[220:221], v[220:221], v[194:195] op_sel_hi:[1,0]
	v_pk_mul_f32 v[222:223], v[222:223], v[194:195] op_sel_hi:[1,0]
	v_pk_mul_f32 v[224:225], v[224:225], v[194:195] op_sel_hi:[1,0]
	v_pk_mul_f32 v[226:227], v[226:227], v[194:195] op_sel_hi:[1,0]
	v_pk_mul_f32 v[228:229], v[228:229], v[194:195] op_sel_hi:[1,0]
	v_pk_mul_f32 v[230:231], v[230:231], v[194:195] op_sel_hi:[1,0]
	v_pk_mul_f32 v[232:233], v[232:233], v[194:195] op_sel_hi:[1,0]
	v_pk_mul_f32 v[234:235], v[234:235], v[194:195] op_sel_hi:[1,0]
	v_mul_f32_e32 v169, v169, v194
; __device__ __forceinline__ void attn_phase(const bf16_t* Z, const bf16_t* Kb, const bf16_t* Vb, unsigned* MASKb, unsigned* itemcnt, bf16_t* Y, LAS unsigned char* lds, int wave, int lane, int bid, int G) {
;     ...
;             if (tb < te) ATT_LOAD(kA, vA, mA, tb);
;             for (int kt = tb; kt < te; kt += 2) {
;                 { const int k1 = (kt + 1 < te) ? kt + 1 : kt; ATT_LOAD(kB, vB, mB, k1); }
;                 ATT_COMP(kA, vA, mA);
;                 { const int k2 = (kt + 2 < te) ? kt + 2 : te - 1; ATT_LOAD(kA, vA, mA, k2); }
;                 if (kt + 1 < te) ATT_COMP(kB, vB, mB);
;             }
.Lat_nors_b:
	v_mov_b32_e32 v170, v193
	v_sub_f32_e32 v50, v50, v170
	v_exp_f32_e32 v50, v50
	v_sub_f32_e32 v51, v51, v170
	v_exp_f32_e32 v51, v51
	v_sub_f32_e32 v52, v52, v170
	v_add_f32_e32 v196, v50, v51
	v_exp_f32_e32 v52, v52
	v_sub_f32_e32 v53, v53, v170
	v_add_f32_e32 v196, v196, v52
	v_exp_f32_e32 v53, v53
	v_sub_f32_e32 v54, v54, v170
	v_add_f32_e32 v196, v196, v53
	v_exp_f32_e32 v54, v54
	v_sub_f32_e32 v55, v55, v170
	v_add_f32_e32 v196, v196, v54
	v_exp_f32_e32 v55, v55
	v_sub_f32_e32 v56, v56, v170
	v_add_f32_e32 v196, v196, v55
	v_exp_f32_e32 v56, v56
	v_sub_f32_e32 v57, v57, v170
	v_add_f32_e32 v196, v196, v56
	v_exp_f32_e32 v57, v57
	v_sub_f32_e32 v58, v58, v170
	v_add_f32_e32 v196, v196, v57
	v_exp_f32_e32 v58, v58
	v_sub_f32_e32 v59, v59, v170
	v_add_f32_e32 v196, v196, v58
	v_exp_f32_e32 v59, v59
	v_sub_f32_e32 v60, v60, v170
	v_add_f32_e32 v196, v196, v59
	v_exp_f32_e32 v60, v60
	v_sub_f32_e32 v61, v61, v170
	v_add_f32_e32 v196, v196, v60
	v_exp_f32_e32 v61, v61
	v_sub_f32_e32 v62, v62, v170
	v_add_f32_e32 v196, v196, v61
	v_exp_f32_e32 v62, v62
	v_sub_f32_e32 v63, v63, v170
	v_add_f32_e32 v196, v196, v62
	v_exp_f32_e32 v63, v63
	v_sub_f32_e32 v64, v64, v170
	v_add_f32_e32 v196, v196, v63
	v_exp_f32_e32 v64, v64
	v_sub_f32_e32 v65, v65, v170
	v_add_f32_e32 v196, v196, v64
	v_exp_f32_e32 v65, v65
	s_nop 0
	v_add_f32_e32 v196, v196, v65
	v_add_f32_e32 v169, v169, v196
	v_cvt_pk_bf16_f32 v182, v50, v51
	v_cvt_pk_bf16_f32 v183, v52, v53
	v_cvt_pk_bf16_f32 v184, v54, v55
	v_cvt_pk_bf16_f32 v185, v56, v57
	v_cvt_pk_bf16_f32 v186, v58, v59
	v_cvt_pk_bf16_f32 v187, v60, v61
	v_cvt_pk_bf16_f32 v188, v62, v63
	v_cvt_pk_bf16_f32 v189, v64, v65
	s_waitcnt vmcnt(6)
	v_mfma_f32_32x32x16_bf16 v[18:33], v[98:101], v[130:133], v[18:33]
	v_mfma_f32_32x32x16_bf16 v[2:17], v[106:109], v[130:133], v[2:17]
	v_mfma_f32_32x32x16_bf16 v[18:33], v[102:105], v[134:137], v[18:33]
	v_mfma_f32_32x32x16_bf16 v[2:17], v[110:113], v[134:137], v[2:17]
	v_mfma_f32_32x32x16_bf16 v[198:213], v[98:101], v[182:185], v[198:213]
	v_mfma_f32_32x32x16_bf16 v[220:235], v[106:109], v[182:185], v[220:235]
	v_mfma_f32_32x32x16_bf16 v[198:213], v[102:105], v[186:189], v[198:213]
	v_mfma_f32_32x32x16_bf16 v[220:235], v[110:113], v[186:189], v[220:235]
	s_add_u32 s28, s10, s27
	s_addc_u32 s29, s11, 0
	global_load_dwordx4 v[98:101], v175, s[28:29]
	global_load_dwordx4 v[102:105], v175, s[28:29] offset:1024
	global_load_dwordx4 v[106:109], v175, s[28:29] offset:2048
	global_load_dwordx4 v[110:113], v175, s[28:29] offset:3072
	s_add_i32 s8, s8, 1
	s_cmp_lt_i32 s8, s19
	s_cbranch_scc1 .Lat_loop
	s_waitcnt vmcnt(0)
	s_mov_b32 s35, 0

; __device__ __forceinline__ unsigned cvt_pk_bf16(float lo, float hi) { unsigned r; asm volatile("v_cvt_pk_bf16_f32 %0, %1, %2" : "=v"(r) : "v"(lo), "v"(hi)); return r; }
; #define LAS __attribute__((address_space(3)))
; #define LDS_WAIT() asm volatile("s_waitcnt lgkmcnt(0)" ::: "memory")
; __device__ __forceinline__ float swap32(float v, int hi) { auto rr = __builtin_amdgcn_permlane32_swap(__float_as_uint(v), __float_as_uint(v), false, false); return hi ? __uint_as_float(rr[0]) : __uint_as_float(rr[1]); }
; __device__ __forceinline__ void attn_phase(const bf16_t* Z, const bf16_t* Kb, const bf16_t* Vb, unsigned* MASKb, unsigned* itemcnt, bf16_t* Y, LAS unsigned char* lds, int wave, int lane, int bid, int G) {
;     ...
;             const float lt = l + swap32(l, hi);
;             if (half == 1) {
; #pragma unroll
;                 for (int r = 0; r < 16; ++r) { mo[r * 64 + lane] = o0[r]; mo[(16 + r) * 64 + lane] = o1[r]; }
;                 mml[lane] = m; mml[64 + lane] = lt;
;             }
;             __syncthreads();
;             if (half == 0) {
;                 const float m1 = mml[lane], l1 = mml[64 + lane];
;                 const float mn = fmaxf(m, m1), a0 = __builtin_amdgcn_exp2f(m - mn), a1 = __builtin_amdgcn_exp2f(m1 - mn);
;                 const float inv = __builtin_amdgcn_rcpf(lt * a0 + l1 * a1), f0 = a0 * inv, f1 = a1 * inv;
; #pragma unroll
;                 for (int r = 0; r < 16; ++r) { o0[r] = o0[r] * f0 + mo[r * 64 + lane] * f1; o1[r] = o1[r] * f0 + mo[(16 + r) * 64 + lane] * f1; }
; #pragma unroll
;                 for (int r = 0; r < 16; r += 2) {
;                     const int d = (r & 3) + 8 * (r >> 2) + 4 * hi;
;                     *(LAS unsigned*)(ost + ql * 72 + d) = cvt_pk_bf16(o0[r], o0[r + 1]);
;                     *(LAS unsigned*)(ost + ql * 72 + 32 + d) = cvt_pk_bf16(o1[r], o1[r + 1]);
;                 }
;                 LDS_WAIT();
;                 bf16_t* yo = Y + ((size_t)b * SEQ + qb * 32 + (lane >> 1)) * DM + 512 + h * 64 + (lane & 1) * 32;
; #pragma unroll
;                 for (int k = 0; k < 4; ++k) { const u32x4 v = *(const LAS u32x4*)(ost + (lane >> 1) * 72 + (lane & 1) * 32 + k * 8); *(u32x4*)(yo + k * 8) = v; }
;             }
;             __syncthreads();
;         }
;     }
.Lat_e69:
	s_barrier
	s_cmp_eq_u32 s35, 1
	s_cbranch_scc1 .Lat_epi_done
	s_mov_b32 s35, 1
	v_mov_b32_e32 v18, v198
	v_mov_b32_e32 v19, v199
	v_mov_b32_e32 v20, v200
	v_mov_b32_e32 v21, v201
	v_mov_b32_e32 v22, v202
	v_mov_b32_e32 v23, v203
	v_mov_b32_e32 v24, v204
	v_mov_b32_e32 v25, v205
	v_mov_b32_e32 v26, v206
	v_mov_b32_e32 v27, v207
	v_mov_b32_e32 v28, v208
	v_mov_b32_e32 v29, v209
	v_mov_b32_e32 v30, v210
	v_mov_b32_e32 v31, v211
	v_mov_b32_e32 v32, v212
	v_mov_b32_e32 v33, v213
	v_mov_b32_e32 v2, v220
	v_mov_b32_e32 v3, v221
	v_mov_b32_e32 v4, v222
	v_mov_b32_e32 v5, v223
	v_mov_b32_e32 v6, v224
	v_mov_b32_e32 v7, v225
	v_mov_b32_e32 v8, v226
	v_mov_b32_e32 v9, v227
	v_mov_b32_e32 v10, v228
	v_mov_b32_e32 v11, v229
	v_mov_b32_e32 v12, v230
	v_mov_b32_e32 v13, v231
	v_mov_b32_e32 v14, v232
	v_mov_b32_e32 v15, v233
	v_mov_b32_e32 v16, v234
	v_mov_b32_e32 v17, v235
	v_mov_b32_e32 v168, v170
	v_mov_b32_e32 v167, v169
	s_add_i32 s18, s18, 32
	s_branch .Lat_epi
.Lat_epi_done:
	s_add_i32 s25, s25, s97
	s_cmpk_gt_i32 s25, 0xff
	s_barrier
	s_cbranch_scc1 .LBB0_110
	s_branch .Lat_pu
